# v59: v53 with the non-leader back-off before the first grid-barrier poll shortened (s_sleep 24 instead of 32)
# speedup vs baseline: 1.0021x; 1.0021x over previous
; __device__ __forceinline__ unsigned xb_ld(unsigned* p)              { return __hip_atomic_load(p, __ATOMIC_RELAXED, __HIP_MEMORY_SCOPE_AGENT); }
; #define XB_SPIN(cond, bar) do { unsigned _sp = 0; while (cond) { __builtin_amdgcn_s_sleep(1); \
;     if ((++_sp & 255u) == 0u) { if (xb_ld(&(bar)[XB_TMO])) break; if (_sp > XB_SPIN_CAP) { atomicAdd(&(bar)[XB_TMO], 1u); break; } } } } while (0)
; __device__ __forceinline__ void xcd_barrier(const XcdBarrier& b) {
;     ...
;             XB_SPIN(xb_ld(&bar[XB_XGEN(b.x)]) == gen, bar);
.Lxb0_wait:
	s_sleep 24
